# v42: v41 + conv depthwise FMA section rewritten with packed fp32 FMAs (two output tokens per instruction, reversed resident weights)
# baseline (speedup 1.0000x reference)
; __device__ __forceinline__ void conv_phase(LAS unsigned char* lds, const bf16_t* P, const float* cw, const float* cb, const float* ng, const float* nb, bf16_t* CAT, int bid, int G, const int tid) {
;     ...
;             const int c = tid & 127, tb = tid >> 7;
;             float wj[31];
; #pragma unroll
;             for (int j = 0; j < 31; ++j) wj[j] = cw[j * 1024 + g * 128 + c];
;             const float bias = cb[g * 128 + c];
;             float acc[16];
; #pragma unroll
;             for (int o = 0; o < 16; ++o) acc[o] = bias;
; #pragma unroll
;             for (int i = 0; i < 46; ++i) {
;                 const float z = zs[(tb * 16 + i) * 128 + c];
; #pragma unroll
;                 for (int o = 0; o < 16; ++o) { const int j = i - o; if (j >= 0 && j <= 30) acc[o] += wj[j] * z; }
.LBB0_170:
	s_and_b32 s30, s35, 0x380
	s_cmp_eq_u32 s30, s63
	s_cbranch_scc1 .Lconv_wok
	s_mov_b32 s63, s30
	v_or_b32_e32 v253, s30, v39
	v_lshlrev_b32_e32 v253, 2, v253
	s_mov_b64 s[64:65], s[4:5]
	global_load_dword v226, v253, s[64:65]
	s_add_u32 s64, s64, 0x1000
	s_addc_u32 s65, s65, 0
	global_load_dword v225, v253, s[64:65]
	s_add_u32 s64, s64, 0x1000
	s_addc_u32 s65, s65, 0
	global_load_dword v224, v253, s[64:65]
	s_add_u32 s64, s64, 0x1000
	s_addc_u32 s65, s65, 0
	global_load_dword v223, v253, s[64:65]
	s_add_u32 s64, s64, 0x1000
	s_addc_u32 s65, s65, 0
	global_load_dword v222, v253, s[64:65]
	s_add_u32 s64, s64, 0x1000
	s_addc_u32 s65, s65, 0
	global_load_dword v221, v253, s[64:65]
	s_add_u32 s64, s64, 0x1000
	s_addc_u32 s65, s65, 0
	global_load_dword v220, v253, s[64:65]
	s_add_u32 s64, s64, 0x1000
	s_addc_u32 s65, s65, 0
	global_load_dword v219, v253, s[64:65]
	s_add_u32 s64, s64, 0x1000
	s_addc_u32 s65, s65, 0
	global_load_dword v218, v253, s[64:65]
	s_add_u32 s64, s64, 0x1000
	s_addc_u32 s65, s65, 0
	global_load_dword v217, v253, s[64:65]
	s_add_u32 s64, s64, 0x1000
	s_addc_u32 s65, s65, 0
	global_load_dword v216, v253, s[64:65]
	s_add_u32 s64, s64, 0x1000
	s_addc_u32 s65, s65, 0
	global_load_dword v215, v253, s[64:65]
	s_add_u32 s64, s64, 0x1000
	s_addc_u32 s65, s65, 0
	global_load_dword v214, v253, s[64:65]
	s_add_u32 s64, s64, 0x1000
	s_addc_u32 s65, s65, 0
	global_load_dword v213, v253, s[64:65]
	s_add_u32 s64, s64, 0x1000
	s_addc_u32 s65, s65, 0
	global_load_dword v212, v253, s[64:65]
	s_add_u32 s64, s64, 0x1000
	s_addc_u32 s65, s65, 0
	global_load_dword v211, v253, s[64:65]
	s_add_u32 s64, s64, 0x1000
	s_addc_u32 s65, s65, 0
	global_load_dword v210, v253, s[64:65]
	s_add_u32 s64, s64, 0x1000
	s_addc_u32 s65, s65, 0
	global_load_dword v209, v253, s[64:65]
	s_add_u32 s64, s64, 0x1000
	s_addc_u32 s65, s65, 0
	global_load_dword v208, v253, s[64:65]
	s_add_u32 s64, s64, 0x1000
	s_addc_u32 s65, s65, 0
	global_load_dword v207, v253, s[64:65]
	s_add_u32 s64, s64, 0x1000
	s_addc_u32 s65, s65, 0
	global_load_dword v206, v253, s[64:65]
	s_add_u32 s64, s64, 0x1000
	s_addc_u32 s65, s65, 0
	global_load_dword v205, v253, s[64:65]
	s_add_u32 s64, s64, 0x1000
	s_addc_u32 s65, s65, 0
	global_load_dword v204, v253, s[64:65]
	s_add_u32 s64, s64, 0x1000
	s_addc_u32 s65, s65, 0
	global_load_dword v203, v253, s[64:65]
	s_add_u32 s64, s64, 0x1000
	s_addc_u32 s65, s65, 0
	global_load_dword v202, v253, s[64:65]
	s_add_u32 s64, s64, 0x1000
	s_addc_u32 s65, s65, 0
	global_load_dword v201, v253, s[64:65]
	s_add_u32 s64, s64, 0x1000
	s_addc_u32 s65, s65, 0
	global_load_dword v200, v253, s[64:65]
	s_add_u32 s64, s64, 0x1000
	s_addc_u32 s65, s65, 0
	global_load_dword v199, v253, s[64:65]
	s_add_u32 s64, s64, 0x1000
	s_addc_u32 s65, s65, 0
	global_load_dword v198, v253, s[64:65]
	s_add_u32 s64, s64, 0x1000
	s_addc_u32 s65, s65, 0
	global_load_dword v197, v253, s[64:65]
	s_add_u32 s64, s64, 0x1000
	s_addc_u32 s65, s65, 0
	global_load_dword v196, v253, s[64:65]
	global_load_dword v252, v253, s[6:7]
	v_mov_b32_e32 v195, 0
	v_mov_b32_e32 v227, 0
	s_lshl_b32 s64, s30, 2
	s_mov_b32 s65, 0
	v_lshl_add_u64 v[154:155], v[26:27], 0, s[64:65]
	global_load_dwordx2 v[150:151], v[154:155], off
	v_lshl_add_u64 v[154:155], v[28:29], 0, s[64:65]
	global_load_dwordx2 v[152:153], v[154:155], off
	s_waitcnt vmcnt(0)
.Lconv_wok:
	v_or_b32_e32 v31, s30, v39
	v_lshlrev_b32_e32 v176, 2, v31
	s_and_b32 s31, s34, 0xffffffc0
	s_mov_b32 s34, s15
	s_mov_b32 s35, s17
	s_lshl_b32 s26, s30, 2
	s_andn2_b64 vcc, exec, s[20:21]
	ds_read2st64_b32 v[172:173], v40 offset0:0 offset1:2
	ds_read2st64_b32 v[174:175], v40 offset0:4 offset1:6
	ds_read2st64_b32 v[180:181], v40 offset0:8 offset1:10
	ds_read2st64_b32 v[182:183], v40 offset0:12 offset1:14
	ds_read2st64_b32 v[184:185], v40 offset0:16 offset1:18
	ds_read2st64_b32 v[186:187], v40 offset0:20 offset1:22
	v_mov_b32_e32 v66, v195
	v_mov_b32_e32 v67, v196
	v_mov_b32_e32 v68, v197
	v_mov_b32_e32 v69, v198
	v_mov_b32_e32 v70, v199
	v_mov_b32_e32 v71, v200
	v_mov_b32_e32 v72, v201
	v_mov_b32_e32 v73, v202
	v_mov_b32_e32 v74, v203
	v_mov_b32_e32 v75, v204
	v_mov_b32_e32 v76, v205
	v_mov_b32_e32 v77, v206
	v_mov_b32_e32 v78, v207
	v_mov_b32_e32 v79, v208
	v_mov_b32_e32 v80, v209
	v_mov_b32_e32 v81, v210
	v_mov_b32_e32 v82, v211
	v_mov_b32_e32 v83, v212
	v_mov_b32_e32 v84, v213
	v_mov_b32_e32 v85, v214
	v_mov_b32_e32 v86, v215
	v_mov_b32_e32 v87, v216
	v_mov_b32_e32 v88, v217
	v_mov_b32_e32 v89, v218
	v_mov_b32_e32 v90, v219
	v_mov_b32_e32 v91, v220
	v_mov_b32_e32 v92, v221
	v_mov_b32_e32 v93, v222
	v_mov_b32_e32 v94, v223
	v_mov_b32_e32 v95, v224
	v_mov_b32_e32 v96, v225
	v_mov_b32_e32 v97, v226
	v_mov_b32_e32 v98, v227
	v_mov_b32_e32 v100, v252
	v_mov_b32_e32 v101, v252
	v_mov_b32_e32 v102, v252
	v_mov_b32_e32 v103, v252
	v_mov_b32_e32 v104, v252
	v_mov_b32_e32 v105, v252
	v_mov_b32_e32 v106, v252
	v_mov_b32_e32 v107, v252
	v_mov_b32_e32 v108, v252
	v_mov_b32_e32 v109, v252
	v_mov_b32_e32 v166, v252
	v_mov_b32_e32 v167, v252
	v_mov_b32_e32 v168, v252
	v_mov_b32_e32 v169, v252
	v_mov_b32_e32 v170, v252
	v_mov_b32_e32 v171, v252
	s_waitcnt lgkmcnt(5)
	v_pk_fma_f32 v[100:101], v[226:227], v[172:173], v[100:101] op_sel:[0,0,0] op_sel_hi:[1,0,1]
	v_pk_fma_f32 v[100:101], v[96:97], v[172:173], v[100:101] op_sel:[0,1,0] op_sel_hi:[1,1,1]
	ds_read2st64_b32 v[172:173], v40 offset0:24 offset1:26
	s_waitcnt lgkmcnt(5)
	v_pk_fma_f32 v[100:101], v[224:225], v[174:175], v[100:101] op_sel:[0,0,0] op_sel_hi:[1,0,1]
	v_pk_fma_f32 v[102:103], v[226:227], v[174:175], v[102:103] op_sel:[0,0,0] op_sel_hi:[1,0,1]
	v_pk_fma_f32 v[100:101], v[94:95], v[174:175], v[100:101] op_sel:[0,1,0] op_sel_hi:[1,1,1]
	v_pk_fma_f32 v[102:103], v[96:97], v[174:175], v[102:103] op_sel:[0,1,0] op_sel_hi:[1,1,1]
	ds_read2st64_b32 v[174:175], v40 offset0:28 offset1:30
	s_waitcnt lgkmcnt(5)
; __device__ __forceinline__ void conv_phase(LAS unsigned char* lds, const bf16_t* P, const float* cw, const float* cb, const float* ng, const float* nb, bf16_t* CAT, int bid, int G, const int tid) {
;     ...
;             for (int i = 0; i < 46; ++i) {
;                 const float z = zs[(tb * 16 + i) * 128 + c];
; #pragma unroll
;                 for (int o = 0; o < 16; ++o) { const int j = i - o; if (j >= 0 && j <= 30) acc[o] += wj[j] * z; }
	v_pk_fma_f32 v[100:101], v[222:223], v[180:181], v[100:101] op_sel:[0,0,0] op_sel_hi:[1,0,1]
	v_pk_fma_f32 v[102:103], v[224:225], v[180:181], v[102:103] op_sel:[0,0,0] op_sel_hi:[1,0,1]
	v_pk_fma_f32 v[104:105], v[226:227], v[180:181], v[104:105] op_sel:[0,0,0] op_sel_hi:[1,0,1]
	v_pk_fma_f32 v[100:101], v[92:93], v[180:181], v[100:101] op_sel:[0,1,0] op_sel_hi:[1,1,1]
	v_pk_fma_f32 v[102:103], v[94:95], v[180:181], v[102:103] op_sel:[0,1,0] op_sel_hi:[1,1,1]
	v_pk_fma_f32 v[104:105], v[96:97], v[180:181], v[104:105] op_sel:[0,1,0] op_sel_hi:[1,1,1]
	ds_read2st64_b32 v[180:181], v40 offset0:32 offset1:34
	s_waitcnt lgkmcnt(5)
	v_pk_fma_f32 v[100:101], v[220:221], v[182:183], v[100:101] op_sel:[0,0,0] op_sel_hi:[1,0,1]
	v_pk_fma_f32 v[102:103], v[222:223], v[182:183], v[102:103] op_sel:[0,0,0] op_sel_hi:[1,0,1]
	v_pk_fma_f32 v[104:105], v[224:225], v[182:183], v[104:105] op_sel:[0,0,0] op_sel_hi:[1,0,1]
	v_pk_fma_f32 v[106:107], v[226:227], v[182:183], v[106:107] op_sel:[0,0,0] op_sel_hi:[1,0,1]
	v_pk_fma_f32 v[100:101], v[90:91], v[182:183], v[100:101] op_sel:[0,1,0] op_sel_hi:[1,1,1]
	v_pk_fma_f32 v[102:103], v[92:93], v[182:183], v[102:103] op_sel:[0,1,0] op_sel_hi:[1,1,1]
	v_pk_fma_f32 v[104:105], v[94:95], v[182:183], v[104:105] op_sel:[0,1,0] op_sel_hi:[1,1,1]
	v_pk_fma_f32 v[106:107], v[96:97], v[182:183], v[106:107] op_sel:[0,1,0] op_sel_hi:[1,1,1]
	ds_read2st64_b32 v[182:183], v40 offset0:36 offset1:38
	s_waitcnt lgkmcnt(5)
	v_pk_fma_f32 v[100:101], v[218:219], v[184:185], v[100:101] op_sel:[0,0,0] op_sel_hi:[1,0,1]
	v_pk_fma_f32 v[102:103], v[220:221], v[184:185], v[102:103] op_sel:[0,0,0] op_sel_hi:[1,0,1]
	v_pk_fma_f32 v[104:105], v[222:223], v[184:185], v[104:105] op_sel:[0,0,0] op_sel_hi:[1,0,1]
	v_pk_fma_f32 v[106:107], v[224:225], v[184:185], v[106:107] op_sel:[0,0,0] op_sel_hi:[1,0,1]
	v_pk_fma_f32 v[108:109], v[226:227], v[184:185], v[108:109] op_sel:[0,0,0] op_sel_hi:[1,0,1]
	v_pk_fma_f32 v[100:101], v[88:89], v[184:185], v[100:101] op_sel:[0,1,0] op_sel_hi:[1,1,1]
	v_pk_fma_f32 v[102:103], v[90:91], v[184:185], v[102:103] op_sel:[0,1,0] op_sel_hi:[1,1,1]
	v_pk_fma_f32 v[104:105], v[92:93], v[184:185], v[104:105] op_sel:[0,1,0] op_sel_hi:[1,1,1]
	v_pk_fma_f32 v[106:107], v[94:95], v[184:185], v[106:107] op_sel:[0,1,0] op_sel_hi:[1,1,1]
	v_pk_fma_f32 v[108:109], v[96:97], v[184:185], v[108:109] op_sel:[0,1,0] op_sel_hi:[1,1,1]
	ds_read2st64_b32 v[184:185], v40 offset0:40 offset1:42
	s_waitcnt lgkmcnt(5)
	v_pk_fma_f32 v[100:101], v[216:217], v[186:187], v[100:101] op_sel:[0,0,0] op_sel_hi:[1,0,1]
	v_pk_fma_f32 v[102:103], v[218:219], v[186:187], v[102:103] op_sel:[0,0,0] op_sel_hi:[1,0,1]
	v_pk_fma_f32 v[104:105], v[220:221], v[186:187], v[104:105] op_sel:[0,0,0] op_sel_hi:[1,0,1]
	v_pk_fma_f32 v[106:107], v[222:223], v[186:187], v[106:107] op_sel:[0,0,0] op_sel_hi:[1,0,1]
	v_pk_fma_f32 v[108:109], v[224:225], v[186:187], v[108:109] op_sel:[0,0,0] op_sel_hi:[1,0,1]
	v_pk_fma_f32 v[166:167], v[226:227], v[186:187], v[166:167] op_sel:[0,0,0] op_sel_hi:[1,0,1]
	v_pk_fma_f32 v[100:101], v[86:87], v[186:187], v[100:101] op_sel:[0,1,0] op_sel_hi:[1,1,1]
	v_pk_fma_f32 v[102:103], v[88:89], v[186:187], v[102:103] op_sel:[0,1,0] op_sel_hi:[1,1,1]
	v_pk_fma_f32 v[104:105], v[90:91], v[186:187], v[104:105] op_sel:[0,1,0] op_sel_hi:[1,1,1]
	v_pk_fma_f32 v[106:107], v[92:93], v[186:187], v[106:107] op_sel:[0,1,0] op_sel_hi:[1,1,1]
	v_pk_fma_f32 v[108:109], v[94:95], v[186:187], v[108:109] op_sel:[0,1,0] op_sel_hi:[1,1,1]
	v_pk_fma_f32 v[166:167], v[96:97], v[186:187], v[166:167] op_sel:[0,1,0] op_sel_hi:[1,1,1]
	ds_read2st64_b32 v[186:187], v40 offset0:44 offset1:46
	s_waitcnt lgkmcnt(5)
	v_pk_fma_f32 v[100:101], v[214:215], v[172:173], v[100:101] op_sel:[0,0,0] op_sel_hi:[1,0,1]
	v_pk_fma_f32 v[102:103], v[216:217], v[172:173], v[102:103] op_sel:[0,0,0] op_sel_hi:[1,0,1]
	v_pk_fma_f32 v[104:105], v[218:219], v[172:173], v[104:105] op_sel:[0,0,0] op_sel_hi:[1,0,1]
	v_pk_fma_f32 v[106:107], v[220:221], v[172:173], v[106:107] op_sel:[0,0,0] op_sel_hi:[1,0,1]
	v_pk_fma_f32 v[108:109], v[222:223], v[172:173], v[108:109] op_sel:[0,0,0] op_sel_hi:[1,0,1]
	v_pk_fma_f32 v[166:167], v[224:225], v[172:173], v[166:167] op_sel:[0,0,0] op_sel_hi:[1,0,1]
	v_pk_fma_f32 v[168:169], v[226:227], v[172:173], v[168:169] op_sel:[0,0,0] op_sel_hi:[1,0,1]
	v_pk_fma_f32 v[100:101], v[84:85], v[172:173], v[100:101] op_sel:[0,1,0] op_sel_hi:[1,1,1]
	v_pk_fma_f32 v[102:103], v[86:87], v[172:173], v[102:103] op_sel:[0,1,0] op_sel_hi:[1,1,1]
	v_pk_fma_f32 v[104:105], v[88:89], v[172:173], v[104:105] op_sel:[0,1,0] op_sel_hi:[1,1,1]
	v_pk_fma_f32 v[106:107], v[90:91], v[172:173], v[106:107] op_sel:[0,1,0] op_sel_hi:[1,1,1]
	v_pk_fma_f32 v[108:109], v[92:93], v[172:173], v[108:109] op_sel:[0,1,0] op_sel_hi:[1,1,1]
	v_pk_fma_f32 v[166:167], v[94:95], v[172:173], v[166:167] op_sel:[0,1,0] op_sel_hi:[1,1,1]
	v_pk_fma_f32 v[168:169], v[96:97], v[172:173], v[168:169] op_sel:[0,1,0] op_sel_hi:[1,1,1]
	ds_read2st64_b32 v[172:173], v40 offset0:48 offset1:50
	s_waitcnt lgkmcnt(5)
; __device__ __forceinline__ void conv_phase(LAS unsigned char* lds, const bf16_t* P, const float* cw, const float* cb, const float* ng, const float* nb, bf16_t* CAT, int bid, int G, const int tid) {
;     ...
;             for (int i = 0; i < 46; ++i) {
;                 const float z = zs[(tb * 16 + i) * 128 + c];
; #pragma unroll
;                 for (int o = 0; o < 16; ++o) { const int j = i - o; if (j >= 0 && j <= 30) acc[o] += wj[j] * z; }
	v_pk_fma_f32 v[100:101], v[212:213], v[174:175], v[100:101] op_sel:[0,0,0] op_sel_hi:[1,0,1]
	v_pk_fma_f32 v[102:103], v[214:215], v[174:175], v[102:103] op_sel:[0,0,0] op_sel_hi:[1,0,1]
	v_pk_fma_f32 v[104:105], v[216:217], v[174:175], v[104:105] op_sel:[0,0,0] op_sel_hi:[1,0,1]
	v_pk_fma_f32 v[106:107], v[218:219], v[174:175], v[106:107] op_sel:[0,0,0] op_sel_hi:[1,0,1]
	v_pk_fma_f32 v[108:109], v[220:221], v[174:175], v[108:109] op_sel:[0,0,0] op_sel_hi:[1,0,1]
	v_pk_fma_f32 v[166:167], v[222:223], v[174:175], v[166:167] op_sel:[0,0,0] op_sel_hi:[1,0,1]
	v_pk_fma_f32 v[168:169], v[224:225], v[174:175], v[168:169] op_sel:[0,0,0] op_sel_hi:[1,0,1]
	v_pk_fma_f32 v[170:171], v[226:227], v[174:175], v[170:171] op_sel:[0,0,0] op_sel_hi:[1,0,1]
	v_pk_fma_f32 v[100:101], v[82:83], v[174:175], v[100:101] op_sel:[0,1,0] op_sel_hi:[1,1,1]
	v_pk_fma_f32 v[102:103], v[84:85], v[174:175], v[102:103] op_sel:[0,1,0] op_sel_hi:[1,1,1]
	v_pk_fma_f32 v[104:105], v[86:87], v[174:175], v[104:105] op_sel:[0,1,0] op_sel_hi:[1,1,1]
	v_pk_fma_f32 v[106:107], v[88:89], v[174:175], v[106:107] op_sel:[0,1,0] op_sel_hi:[1,1,1]
	v_pk_fma_f32 v[108:109], v[90:91], v[174:175], v[108:109] op_sel:[0,1,0] op_sel_hi:[1,1,1]
	v_pk_fma_f32 v[166:167], v[92:93], v[174:175], v[166:167] op_sel:[0,1,0] op_sel_hi:[1,1,1]
	v_pk_fma_f32 v[168:169], v[94:95], v[174:175], v[168:169] op_sel:[0,1,0] op_sel_hi:[1,1,1]
	v_pk_fma_f32 v[170:171], v[96:97], v[174:175], v[170:171] op_sel:[0,1,0] op_sel_hi:[1,1,1]
	ds_read2st64_b32 v[174:175], v40 offset0:52 offset1:54
	s_waitcnt lgkmcnt(5)
	v_pk_fma_f32 v[100:101], v[210:211], v[180:181], v[100:101] op_sel:[0,0,0] op_sel_hi:[1,0,1]
	v_pk_fma_f32 v[102:103], v[212:213], v[180:181], v[102:103] op_sel:[0,0,0] op_sel_hi:[1,0,1]
	v_pk_fma_f32 v[104:105], v[214:215], v[180:181], v[104:105] op_sel:[0,0,0] op_sel_hi:[1,0,1]
	v_pk_fma_f32 v[106:107], v[216:217], v[180:181], v[106:107] op_sel:[0,0,0] op_sel_hi:[1,0,1]
	v_pk_fma_f32 v[108:109], v[218:219], v[180:181], v[108:109] op_sel:[0,0,0] op_sel_hi:[1,0,1]
	v_pk_fma_f32 v[166:167], v[220:221], v[180:181], v[166:167] op_sel:[0,0,0] op_sel_hi:[1,0,1]
	v_pk_fma_f32 v[168:169], v[222:223], v[180:181], v[168:169] op_sel:[0,0,0] op_sel_hi:[1,0,1]
	v_pk_fma_f32 v[170:171], v[224:225], v[180:181], v[170:171] op_sel:[0,0,0] op_sel_hi:[1,0,1]
	v_pk_fma_f32 v[100:101], v[80:81], v[180:181], v[100:101] op_sel:[0,1,0] op_sel_hi:[1,1,1]
	v_pk_fma_f32 v[102:103], v[82:83], v[180:181], v[102:103] op_sel:[0,1,0] op_sel_hi:[1,1,1]
	v_pk_fma_f32 v[104:105], v[84:85], v[180:181], v[104:105] op_sel:[0,1,0] op_sel_hi:[1,1,1]
	v_pk_fma_f32 v[106:107], v[86:87], v[180:181], v[106:107] op_sel:[0,1,0] op_sel_hi:[1,1,1]
	v_pk_fma_f32 v[108:109], v[88:89], v[180:181], v[108:109] op_sel:[0,1,0] op_sel_hi:[1,1,1]
	v_pk_fma_f32 v[166:167], v[90:91], v[180:181], v[166:167] op_sel:[0,1,0] op_sel_hi:[1,1,1]
	v_pk_fma_f32 v[168:169], v[92:93], v[180:181], v[168:169] op_sel:[0,1,0] op_sel_hi:[1,1,1]
	v_pk_fma_f32 v[170:171], v[94:95], v[180:181], v[170:171] op_sel:[0,1,0] op_sel_hi:[1,1,1]
	ds_read2st64_b32 v[180:181], v40 offset0:56 offset1:58
	s_waitcnt lgkmcnt(5)
	v_pk_fma_f32 v[100:101], v[208:209], v[182:183], v[100:101] op_sel:[0,0,0] op_sel_hi:[1,0,1]
	v_pk_fma_f32 v[102:103], v[210:211], v[182:183], v[102:103] op_sel:[0,0,0] op_sel_hi:[1,0,1]
	v_pk_fma_f32 v[104:105], v[212:213], v[182:183], v[104:105] op_sel:[0,0,0] op_sel_hi:[1,0,1]
	v_pk_fma_f32 v[106:107], v[214:215], v[182:183], v[106:107] op_sel:[0,0,0] op_sel_hi:[1,0,1]
	v_pk_fma_f32 v[108:109], v[216:217], v[182:183], v[108:109] op_sel:[0,0,0] op_sel_hi:[1,0,1]
	v_pk_fma_f32 v[166:167], v[218:219], v[182:183], v[166:167] op_sel:[0,0,0] op_sel_hi:[1,0,1]
	v_pk_fma_f32 v[168:169], v[220:221], v[182:183], v[168:169] op_sel:[0,0,0] op_sel_hi:[1,0,1]
	v_pk_fma_f32 v[170:171], v[222:223], v[182:183], v[170:171] op_sel:[0,0,0] op_sel_hi:[1,0,1]
	v_pk_fma_f32 v[100:101], v[78:79], v[182:183], v[100:101] op_sel:[0,1,0] op_sel_hi:[1,1,1]
	v_pk_fma_f32 v[102:103], v[80:81], v[182:183], v[102:103] op_sel:[0,1,0] op_sel_hi:[1,1,1]
	v_pk_fma_f32 v[104:105], v[82:83], v[182:183], v[104:105] op_sel:[0,1,0] op_sel_hi:[1,1,1]
	v_pk_fma_f32 v[106:107], v[84:85], v[182:183], v[106:107] op_sel:[0,1,0] op_sel_hi:[1,1,1]
	v_pk_fma_f32 v[108:109], v[86:87], v[182:183], v[108:109] op_sel:[0,1,0] op_sel_hi:[1,1,1]
	v_pk_fma_f32 v[166:167], v[88:89], v[182:183], v[166:167] op_sel:[0,1,0] op_sel_hi:[1,1,1]
	v_pk_fma_f32 v[168:169], v[90:91], v[182:183], v[168:169] op_sel:[0,1,0] op_sel_hi:[1,1,1]
	v_pk_fma_f32 v[170:171], v[92:93], v[182:183], v[170:171] op_sel:[0,1,0] op_sel_hi:[1,1,1]
	ds_read2st64_b32 v[182:183], v40 offset0:60 offset1:62
	s_waitcnt lgkmcnt(5)
	v_pk_fma_f32 v[100:101], v[206:207], v[184:185], v[100:101] op_sel:[0,0,0] op_sel_hi:[1,0,1]
	v_pk_fma_f32 v[102:103], v[208:209], v[184:185], v[102:103] op_sel:[0,0,0] op_sel_hi:[1,0,1]
	v_pk_fma_f32 v[104:105], v[210:211], v[184:185], v[104:105] op_sel:[0,0,0] op_sel_hi:[1,0,1]
	v_pk_fma_f32 v[106:107], v[212:213], v[184:185], v[106:107] op_sel:[0,0,0] op_sel_hi:[1,0,1]
	v_pk_fma_f32 v[108:109], v[214:215], v[184:185], v[108:109] op_sel:[0,0,0] op_sel_hi:[1,0,1]
	v_pk_fma_f32 v[166:167], v[216:217], v[184:185], v[166:167] op_sel:[0,0,0] op_sel_hi:[1,0,1]
	v_pk_fma_f32 v[168:169], v[218:219], v[184:185], v[168:169] op_sel:[0,0,0] op_sel_hi:[1,0,1]
	v_pk_fma_f32 v[170:171], v[220:221], v[184:185], v[170:171] op_sel:[0,0,0] op_sel_hi:[1,0,1]
	v_pk_fma_f32 v[100:101], v[76:77], v[184:185], v[100:101] op_sel:[0,1,0] op_sel_hi:[1,1,1]
	v_pk_fma_f32 v[102:103], v[78:79], v[184:185], v[102:103] op_sel:[0,1,0] op_sel_hi:[1,1,1]
	v_pk_fma_f32 v[104:105], v[80:81], v[184:185], v[104:105] op_sel:[0,1,0] op_sel_hi:[1,1,1]
	v_pk_fma_f32 v[106:107], v[82:83], v[184:185], v[106:107] op_sel:[0,1,0] op_sel_hi:[1,1,1]
	v_pk_fma_f32 v[108:109], v[84:85], v[184:185], v[108:109] op_sel:[0,1,0] op_sel_hi:[1,1,1]
	v_pk_fma_f32 v[166:167], v[86:87], v[184:185], v[166:167] op_sel:[0,1,0] op_sel_hi:[1,1,1]
	v_pk_fma_f32 v[168:169], v[88:89], v[184:185], v[168:169] op_sel:[0,1,0] op_sel_hi:[1,1,1]
	v_pk_fma_f32 v[170:171], v[90:91], v[184:185], v[170:171] op_sel:[0,1,0] op_sel_hi:[1,1,1]
	ds_read2st64_b32 v[184:185], v40 offset0:64 offset1:66
	s_waitcnt lgkmcnt(5)
; __device__ __forceinline__ void conv_phase(LAS unsigned char* lds, const bf16_t* P, const float* cw, const float* cb, const float* ng, const float* nb, bf16_t* CAT, int bid, int G, const int tid) {
;     ...
;             for (int i = 0; i < 46; ++i) {
;                 const float z = zs[(tb * 16 + i) * 128 + c];
; #pragma unroll
;                 for (int o = 0; o < 16; ++o) { const int j = i - o; if (j >= 0 && j <= 30) acc[o] += wj[j] * z; }
	v_pk_fma_f32 v[100:101], v[204:205], v[186:187], v[100:101] op_sel:[0,0,0] op_sel_hi:[1,0,1]
	v_pk_fma_f32 v[102:103], v[206:207], v[186:187], v[102:103] op_sel:[0,0,0] op_sel_hi:[1,0,1]
	v_pk_fma_f32 v[104:105], v[208:209], v[186:187], v[104:105] op_sel:[0,0,0] op_sel_hi:[1,0,1]
	v_pk_fma_f32 v[106:107], v[210:211], v[186:187], v[106:107] op_sel:[0,0,0] op_sel_hi:[1,0,1]
	v_pk_fma_f32 v[108:109], v[212:213], v[186:187], v[108:109] op_sel:[0,0,0] op_sel_hi:[1,0,1]
	v_pk_fma_f32 v[166:167], v[214:215], v[186:187], v[166:167] op_sel:[0,0,0] op_sel_hi:[1,0,1]
	v_pk_fma_f32 v[168:169], v[216:217], v[186:187], v[168:169] op_sel:[0,0,0] op_sel_hi:[1,0,1]
	v_pk_fma_f32 v[170:171], v[218:219], v[186:187], v[170:171] op_sel:[0,0,0] op_sel_hi:[1,0,1]
	v_pk_fma_f32 v[100:101], v[74:75], v[186:187], v[100:101] op_sel:[0,1,0] op_sel_hi:[1,1,1]
	v_pk_fma_f32 v[102:103], v[76:77], v[186:187], v[102:103] op_sel:[0,1,0] op_sel_hi:[1,1,1]
	v_pk_fma_f32 v[104:105], v[78:79], v[186:187], v[104:105] op_sel:[0,1,0] op_sel_hi:[1,1,1]
	v_pk_fma_f32 v[106:107], v[80:81], v[186:187], v[106:107] op_sel:[0,1,0] op_sel_hi:[1,1,1]
	v_pk_fma_f32 v[108:109], v[82:83], v[186:187], v[108:109] op_sel:[0,1,0] op_sel_hi:[1,1,1]
	v_pk_fma_f32 v[166:167], v[84:85], v[186:187], v[166:167] op_sel:[0,1,0] op_sel_hi:[1,1,1]
	v_pk_fma_f32 v[168:169], v[86:87], v[186:187], v[168:169] op_sel:[0,1,0] op_sel_hi:[1,1,1]
	v_pk_fma_f32 v[170:171], v[88:89], v[186:187], v[170:171] op_sel:[0,1,0] op_sel_hi:[1,1,1]
	ds_read2st64_b32 v[186:187], v40 offset0:68 offset1:70
	s_waitcnt lgkmcnt(5)
	v_pk_fma_f32 v[100:101], v[202:203], v[172:173], v[100:101] op_sel:[0,0,0] op_sel_hi:[1,0,1]
	v_pk_fma_f32 v[102:103], v[204:205], v[172:173], v[102:103] op_sel:[0,0,0] op_sel_hi:[1,0,1]
	v_pk_fma_f32 v[104:105], v[206:207], v[172:173], v[104:105] op_sel:[0,0,0] op_sel_hi:[1,0,1]
	v_pk_fma_f32 v[106:107], v[208:209], v[172:173], v[106:107] op_sel:[0,0,0] op_sel_hi:[1,0,1]
	v_pk_fma_f32 v[108:109], v[210:211], v[172:173], v[108:109] op_sel:[0,0,0] op_sel_hi:[1,0,1]
	v_pk_fma_f32 v[166:167], v[212:213], v[172:173], v[166:167] op_sel:[0,0,0] op_sel_hi:[1,0,1]
	v_pk_fma_f32 v[168:169], v[214:215], v[172:173], v[168:169] op_sel:[0,0,0] op_sel_hi:[1,0,1]
	v_pk_fma_f32 v[170:171], v[216:217], v[172:173], v[170:171] op_sel:[0,0,0] op_sel_hi:[1,0,1]
	v_pk_fma_f32 v[100:101], v[72:73], v[172:173], v[100:101] op_sel:[0,1,0] op_sel_hi:[1,1,1]
	v_pk_fma_f32 v[102:103], v[74:75], v[172:173], v[102:103] op_sel:[0,1,0] op_sel_hi:[1,1,1]
	v_pk_fma_f32 v[104:105], v[76:77], v[172:173], v[104:105] op_sel:[0,1,0] op_sel_hi:[1,1,1]
	v_pk_fma_f32 v[106:107], v[78:79], v[172:173], v[106:107] op_sel:[0,1,0] op_sel_hi:[1,1,1]
	v_pk_fma_f32 v[108:109], v[80:81], v[172:173], v[108:109] op_sel:[0,1,0] op_sel_hi:[1,1,1]
	v_pk_fma_f32 v[166:167], v[82:83], v[172:173], v[166:167] op_sel:[0,1,0] op_sel_hi:[1,1,1]
	v_pk_fma_f32 v[168:169], v[84:85], v[172:173], v[168:169] op_sel:[0,1,0] op_sel_hi:[1,1,1]
	v_pk_fma_f32 v[170:171], v[86:87], v[172:173], v[170:171] op_sel:[0,1,0] op_sel_hi:[1,1,1]
	ds_read2st64_b32 v[172:173], v40 offset0:72 offset1:74
	s_waitcnt lgkmcnt(5)
	v_pk_fma_f32 v[100:101], v[200:201], v[174:175], v[100:101] op_sel:[0,0,0] op_sel_hi:[1,0,1]
	v_pk_fma_f32 v[102:103], v[202:203], v[174:175], v[102:103] op_sel:[0,0,0] op_sel_hi:[1,0,1]
	v_pk_fma_f32 v[104:105], v[204:205], v[174:175], v[104:105] op_sel:[0,0,0] op_sel_hi:[1,0,1]
	v_pk_fma_f32 v[106:107], v[206:207], v[174:175], v[106:107] op_sel:[0,0,0] op_sel_hi:[1,0,1]
	v_pk_fma_f32 v[108:109], v[208:209], v[174:175], v[108:109] op_sel:[0,0,0] op_sel_hi:[1,0,1]
	v_pk_fma_f32 v[166:167], v[210:211], v[174:175], v[166:167] op_sel:[0,0,0] op_sel_hi:[1,0,1]
	v_pk_fma_f32 v[168:169], v[212:213], v[174:175], v[168:169] op_sel:[0,0,0] op_sel_hi:[1,0,1]
	v_pk_fma_f32 v[170:171], v[214:215], v[174:175], v[170:171] op_sel:[0,0,0] op_sel_hi:[1,0,1]
	v_pk_fma_f32 v[100:101], v[70:71], v[174:175], v[100:101] op_sel:[0,1,0] op_sel_hi:[1,1,1]
	v_pk_fma_f32 v[102:103], v[72:73], v[174:175], v[102:103] op_sel:[0,1,0] op_sel_hi:[1,1,1]
	v_pk_fma_f32 v[104:105], v[74:75], v[174:175], v[104:105] op_sel:[0,1,0] op_sel_hi:[1,1,1]
	v_pk_fma_f32 v[106:107], v[76:77], v[174:175], v[106:107] op_sel:[0,1,0] op_sel_hi:[1,1,1]
	v_pk_fma_f32 v[108:109], v[78:79], v[174:175], v[108:109] op_sel:[0,1,0] op_sel_hi:[1,1,1]
	v_pk_fma_f32 v[166:167], v[80:81], v[174:175], v[166:167] op_sel:[0,1,0] op_sel_hi:[1,1,1]
	v_pk_fma_f32 v[168:169], v[82:83], v[174:175], v[168:169] op_sel:[0,1,0] op_sel_hi:[1,1,1]
	v_pk_fma_f32 v[170:171], v[84:85], v[174:175], v[170:171] op_sel:[0,1,0] op_sel_hi:[1,1,1]
	ds_read2st64_b32 v[174:175], v40 offset0:76 offset1:78
	s_waitcnt lgkmcnt(5)
	v_pk_fma_f32 v[100:101], v[198:199], v[180:181], v[100:101] op_sel:[0,0,0] op_sel_hi:[1,0,1]
	v_pk_fma_f32 v[102:103], v[200:201], v[180:181], v[102:103] op_sel:[0,0,0] op_sel_hi:[1,0,1]
	v_pk_fma_f32 v[104:105], v[202:203], v[180:181], v[104:105] op_sel:[0,0,0] op_sel_hi:[1,0,1]
	v_pk_fma_f32 v[106:107], v[204:205], v[180:181], v[106:107] op_sel:[0,0,0] op_sel_hi:[1,0,1]
	v_pk_fma_f32 v[108:109], v[206:207], v[180:181], v[108:109] op_sel:[0,0,0] op_sel_hi:[1,0,1]
	v_pk_fma_f32 v[166:167], v[208:209], v[180:181], v[166:167] op_sel:[0,0,0] op_sel_hi:[1,0,1]
	v_pk_fma_f32 v[168:169], v[210:211], v[180:181], v[168:169] op_sel:[0,0,0] op_sel_hi:[1,0,1]
	v_pk_fma_f32 v[170:171], v[212:213], v[180:181], v[170:171] op_sel:[0,0,0] op_sel_hi:[1,0,1]
	v_pk_fma_f32 v[100:101], v[68:69], v[180:181], v[100:101] op_sel:[0,1,0] op_sel_hi:[1,1,1]
	v_pk_fma_f32 v[102:103], v[70:71], v[180:181], v[102:103] op_sel:[0,1,0] op_sel_hi:[1,1,1]
	v_pk_fma_f32 v[104:105], v[72:73], v[180:181], v[104:105] op_sel:[0,1,0] op_sel_hi:[1,1,1]
	v_pk_fma_f32 v[106:107], v[74:75], v[180:181], v[106:107] op_sel:[0,1,0] op_sel_hi:[1,1,1]
	v_pk_fma_f32 v[108:109], v[76:77], v[180:181], v[108:109] op_sel:[0,1,0] op_sel_hi:[1,1,1]
	v_pk_fma_f32 v[166:167], v[78:79], v[180:181], v[166:167] op_sel:[0,1,0] op_sel_hi:[1,1,1]
	v_pk_fma_f32 v[168:169], v[80:81], v[180:181], v[168:169] op_sel:[0,1,0] op_sel_hi:[1,1,1]
	v_pk_fma_f32 v[170:171], v[82:83], v[180:181], v[170:171] op_sel:[0,1,0] op_sel_hi:[1,1,1]
	ds_read2st64_b32 v[180:181], v40 offset0:80 offset1:82
	s_waitcnt lgkmcnt(5)
; __device__ __forceinline__ void conv_phase(LAS unsigned char* lds, const bf16_t* P, const float* cw, const float* cb, const float* ng, const float* nb, bf16_t* CAT, int bid, int G, const int tid) {
;     ...
;             for (int i = 0; i < 46; ++i) {
;                 const float z = zs[(tb * 16 + i) * 128 + c];
; #pragma unroll
;                 for (int o = 0; o < 16; ++o) { const int j = i - o; if (j >= 0 && j <= 30) acc[o] += wj[j] * z; }
	v_pk_fma_f32 v[100:101], v[196:197], v[182:183], v[100:101] op_sel:[0,0,0] op_sel_hi:[1,0,1]
	v_pk_fma_f32 v[102:103], v[198:199], v[182:183], v[102:103] op_sel:[0,0,0] op_sel_hi:[1,0,1]
	v_pk_fma_f32 v[104:105], v[200:201], v[182:183], v[104:105] op_sel:[0,0,0] op_sel_hi:[1,0,1]
	v_pk_fma_f32 v[106:107], v[202:203], v[182:183], v[106:107] op_sel:[0,0,0] op_sel_hi:[1,0,1]
	v_pk_fma_f32 v[108:109], v[204:205], v[182:183], v[108:109] op_sel:[0,0,0] op_sel_hi:[1,0,1]
	v_pk_fma_f32 v[166:167], v[206:207], v[182:183], v[166:167] op_sel:[0,0,0] op_sel_hi:[1,0,1]
	v_pk_fma_f32 v[168:169], v[208:209], v[182:183], v[168:169] op_sel:[0,0,0] op_sel_hi:[1,0,1]
	v_pk_fma_f32 v[170:171], v[210:211], v[182:183], v[170:171] op_sel:[0,0,0] op_sel_hi:[1,0,1]
	v_pk_fma_f32 v[100:101], v[66:67], v[182:183], v[100:101] op_sel:[0,1,0] op_sel_hi:[1,1,1]
	v_pk_fma_f32 v[102:103], v[68:69], v[182:183], v[102:103] op_sel:[0,1,0] op_sel_hi:[1,1,1]
	v_pk_fma_f32 v[104:105], v[70:71], v[182:183], v[104:105] op_sel:[0,1,0] op_sel_hi:[1,1,1]
	v_pk_fma_f32 v[106:107], v[72:73], v[182:183], v[106:107] op_sel:[0,1,0] op_sel_hi:[1,1,1]
	v_pk_fma_f32 v[108:109], v[74:75], v[182:183], v[108:109] op_sel:[0,1,0] op_sel_hi:[1,1,1]
	v_pk_fma_f32 v[166:167], v[76:77], v[182:183], v[166:167] op_sel:[0,1,0] op_sel_hi:[1,1,1]
	v_pk_fma_f32 v[168:169], v[78:79], v[182:183], v[168:169] op_sel:[0,1,0] op_sel_hi:[1,1,1]
	v_pk_fma_f32 v[170:171], v[80:81], v[182:183], v[170:171] op_sel:[0,1,0] op_sel_hi:[1,1,1]
	ds_read2st64_b32 v[182:183], v40 offset0:84 offset1:86
	s_waitcnt lgkmcnt(5)
	v_pk_fma_f32 v[102:103], v[196:197], v[184:185], v[102:103] op_sel:[0,0,0] op_sel_hi:[1,0,1]
	v_pk_fma_f32 v[104:105], v[198:199], v[184:185], v[104:105] op_sel:[0,0,0] op_sel_hi:[1,0,1]
	v_pk_fma_f32 v[106:107], v[200:201], v[184:185], v[106:107] op_sel:[0,0,0] op_sel_hi:[1,0,1]
	v_pk_fma_f32 v[108:109], v[202:203], v[184:185], v[108:109] op_sel:[0,0,0] op_sel_hi:[1,0,1]
	v_pk_fma_f32 v[166:167], v[204:205], v[184:185], v[166:167] op_sel:[0,0,0] op_sel_hi:[1,0,1]
	v_pk_fma_f32 v[168:169], v[206:207], v[184:185], v[168:169] op_sel:[0,0,0] op_sel_hi:[1,0,1]
	v_pk_fma_f32 v[170:171], v[208:209], v[184:185], v[170:171] op_sel:[0,0,0] op_sel_hi:[1,0,1]
	v_pk_fma_f32 v[102:103], v[66:67], v[184:185], v[102:103] op_sel:[0,1,0] op_sel_hi:[1,1,1]
	v_pk_fma_f32 v[104:105], v[68:69], v[184:185], v[104:105] op_sel:[0,1,0] op_sel_hi:[1,1,1]
	v_pk_fma_f32 v[106:107], v[70:71], v[184:185], v[106:107] op_sel:[0,1,0] op_sel_hi:[1,1,1]
	v_pk_fma_f32 v[108:109], v[72:73], v[184:185], v[108:109] op_sel:[0,1,0] op_sel_hi:[1,1,1]
	v_pk_fma_f32 v[166:167], v[74:75], v[184:185], v[166:167] op_sel:[0,1,0] op_sel_hi:[1,1,1]
	v_pk_fma_f32 v[168:169], v[76:77], v[184:185], v[168:169] op_sel:[0,1,0] op_sel_hi:[1,1,1]
	v_pk_fma_f32 v[170:171], v[78:79], v[184:185], v[170:171] op_sel:[0,1,0] op_sel_hi:[1,1,1]
	ds_read2st64_b32 v[184:185], v40 offset0:88 offset1:90
	s_waitcnt lgkmcnt(5)
	v_pk_fma_f32 v[104:105], v[196:197], v[186:187], v[104:105] op_sel:[0,0,0] op_sel_hi:[1,0,1]
	v_pk_fma_f32 v[106:107], v[198:199], v[186:187], v[106:107] op_sel:[0,0,0] op_sel_hi:[1,0,1]
	v_pk_fma_f32 v[108:109], v[200:201], v[186:187], v[108:109] op_sel:[0,0,0] op_sel_hi:[1,0,1]
	v_pk_fma_f32 v[166:167], v[202:203], v[186:187], v[166:167] op_sel:[0,0,0] op_sel_hi:[1,0,1]
	v_pk_fma_f32 v[168:169], v[204:205], v[186:187], v[168:169] op_sel:[0,0,0] op_sel_hi:[1,0,1]
	v_pk_fma_f32 v[170:171], v[206:207], v[186:187], v[170:171] op_sel:[0,0,0] op_sel_hi:[1,0,1]
	v_pk_fma_f32 v[104:105], v[66:67], v[186:187], v[104:105] op_sel:[0,1,0] op_sel_hi:[1,1,1]
	v_pk_fma_f32 v[106:107], v[68:69], v[186:187], v[106:107] op_sel:[0,1,0] op_sel_hi:[1,1,1]
	v_pk_fma_f32 v[108:109], v[70:71], v[186:187], v[108:109] op_sel:[0,1,0] op_sel_hi:[1,1,1]
	v_pk_fma_f32 v[166:167], v[72:73], v[186:187], v[166:167] op_sel:[0,1,0] op_sel_hi:[1,1,1]
	v_pk_fma_f32 v[168:169], v[74:75], v[186:187], v[168:169] op_sel:[0,1,0] op_sel_hi:[1,1,1]
	v_pk_fma_f32 v[170:171], v[76:77], v[186:187], v[170:171] op_sel:[0,1,0] op_sel_hi:[1,1,1]
	s_waitcnt lgkmcnt(4)
	v_pk_fma_f32 v[106:107], v[196:197], v[172:173], v[106:107] op_sel:[0,0,0] op_sel_hi:[1,0,1]
	v_pk_fma_f32 v[108:109], v[198:199], v[172:173], v[108:109] op_sel:[0,0,0] op_sel_hi:[1,0,1]
	v_pk_fma_f32 v[166:167], v[200:201], v[172:173], v[166:167] op_sel:[0,0,0] op_sel_hi:[1,0,1]
	v_pk_fma_f32 v[168:169], v[202:203], v[172:173], v[168:169] op_sel:[0,0,0] op_sel_hi:[1,0,1]
	v_pk_fma_f32 v[170:171], v[204:205], v[172:173], v[170:171] op_sel:[0,0,0] op_sel_hi:[1,0,1]
	v_pk_fma_f32 v[106:107], v[66:67], v[172:173], v[106:107] op_sel:[0,1,0] op_sel_hi:[1,1,1]
	v_pk_fma_f32 v[108:109], v[68:69], v[172:173], v[108:109] op_sel:[0,1,0] op_sel_hi:[1,1,1]
	v_pk_fma_f32 v[166:167], v[70:71], v[172:173], v[166:167] op_sel:[0,1,0] op_sel_hi:[1,1,1]
	v_pk_fma_f32 v[168:169], v[72:73], v[172:173], v[168:169] op_sel:[0,1,0] op_sel_hi:[1,1,1]
	v_pk_fma_f32 v[170:171], v[74:75], v[172:173], v[170:171] op_sel:[0,1,0] op_sel_hi:[1,1,1]
	s_waitcnt lgkmcnt(3)
	v_pk_fma_f32 v[108:109], v[196:197], v[174:175], v[108:109] op_sel:[0,0,0] op_sel_hi:[1,0,1]
	v_pk_fma_f32 v[166:167], v[198:199], v[174:175], v[166:167] op_sel:[0,0,0] op_sel_hi:[1,0,1]
	v_pk_fma_f32 v[168:169], v[200:201], v[174:175], v[168:169] op_sel:[0,0,0] op_sel_hi:[1,0,1]
	v_pk_fma_f32 v[170:171], v[202:203], v[174:175], v[170:171] op_sel:[0,0,0] op_sel_hi:[1,0,1]
	v_pk_fma_f32 v[108:109], v[66:67], v[174:175], v[108:109] op_sel:[0,1,0] op_sel_hi:[1,1,1]
	v_pk_fma_f32 v[166:167], v[68:69], v[174:175], v[166:167] op_sel:[0,1,0] op_sel_hi:[1,1,1]
	v_pk_fma_f32 v[168:169], v[70:71], v[174:175], v[168:169] op_sel:[0,1,0] op_sel_hi:[1,1,1]
	v_pk_fma_f32 v[170:171], v[72:73], v[174:175], v[170:171] op_sel:[0,1,0] op_sel_hi:[1,1,1]
	s_waitcnt lgkmcnt(2)
; #define LAS __attribute__((address_space(3)))
; __device__ __forceinline__ void conv_phase(LAS unsigned char* lds, const bf16_t* P, const float* cw, const float* cb, const float* ng, const float* nb, bf16_t* CAT, int bid, int G, const int tid) {
;     ...
;             for (int i = 0; i < 46; ++i) {
;                 const float z = zs[(tb * 16 + i) * 128 + c];
; #pragma unroll
;                 for (int o = 0; o < 16; ++o) { const int j = i - o; if (j >= 0 && j <= 30) acc[o] += wj[j] * z; }
;             }
; #pragma unroll
;             for (int o = 0; o < 16; ++o) co[(tb * 16 + o) * 128 + c] = acc[o];
;         }
;         __syncthreads();
;         {
;             const f32x2 gg = *(const f32x2*)(ng + g * 128 + 2 * lane), bb = *(const f32x2*)(nb + g * 128 + 2 * lane);
; #pragma unroll
;             for (int k = 0; k < 8; ++k) {
;                 const int tok = w * 8 + k;
;                 const f32x2 v = *(const LAS f32x2*)(co + tok * 128 + 2 * lane);
;                 const float mean = wave_sum(v[0] + v[1]) * (1.0f / 128.0f);
	v_pk_fma_f32 v[166:167], v[196:197], v[180:181], v[166:167] op_sel:[0,0,0] op_sel_hi:[1,0,1]
	v_pk_fma_f32 v[168:169], v[198:199], v[180:181], v[168:169] op_sel:[0,0,0] op_sel_hi:[1,0,1]
	v_pk_fma_f32 v[170:171], v[200:201], v[180:181], v[170:171] op_sel:[0,0,0] op_sel_hi:[1,0,1]
	v_pk_fma_f32 v[166:167], v[66:67], v[180:181], v[166:167] op_sel:[0,1,0] op_sel_hi:[1,1,1]
	v_pk_fma_f32 v[168:169], v[68:69], v[180:181], v[168:169] op_sel:[0,1,0] op_sel_hi:[1,1,1]
	v_pk_fma_f32 v[170:171], v[70:71], v[180:181], v[170:171] op_sel:[0,1,0] op_sel_hi:[1,1,1]
	s_waitcnt lgkmcnt(1)
	v_pk_fma_f32 v[168:169], v[196:197], v[182:183], v[168:169] op_sel:[0,0,0] op_sel_hi:[1,0,1]
	v_pk_fma_f32 v[170:171], v[198:199], v[182:183], v[170:171] op_sel:[0,0,0] op_sel_hi:[1,0,1]
	v_pk_fma_f32 v[168:169], v[66:67], v[182:183], v[168:169] op_sel:[0,1,0] op_sel_hi:[1,1,1]
	v_pk_fma_f32 v[170:171], v[68:69], v[182:183], v[170:171] op_sel:[0,1,0] op_sel_hi:[1,1,1]
	s_waitcnt lgkmcnt(0)
	v_pk_fma_f32 v[170:171], v[196:197], v[184:185], v[170:171] op_sel:[0,0,0] op_sel_hi:[1,0,1]
	v_pk_fma_f32 v[170:171], v[66:67], v[184:185], v[170:171] op_sel:[0,1,0] op_sel_hi:[1,1,1]
	ds_write2st64_b32 v40, v100, v101 offset0:188 offset1:190
	ds_write2st64_b32 v40, v102, v103 offset0:192 offset1:194
	ds_write2st64_b32 v40, v104, v105 offset0:196 offset1:198
	ds_write2st64_b32 v40, v106, v107 offset0:200 offset1:202
	ds_write2st64_b32 v40, v108, v109 offset0:204 offset1:206
	ds_write2st64_b32 v40, v166, v167 offset0:208 offset1:210
	ds_write2st64_b32 v40, v168, v169 offset0:212 offset1:214
	ds_write2st64_b32 v40, v170, v171 offset0:216 offset1:218
	s_waitcnt lgkmcnt(0)
	s_barrier
	s_lshl_b32 s26, s30, 1
	v_mov_b32_e32 v31, v177
	ds_read_b64 v[110:111], v58 offset:48128
	ds_read_b64 v[112:113], v59 offset:48128
	ds_read_b64 v[114:115], v60 offset:48128
	ds_read_b64 v[116:117], v61 offset:48128
	ds_read_b64 v[118:119], v62 offset:48128
	ds_read_b64 v[120:121], v63 offset:48128
	ds_read_b64 v[122:123], v64 offset:48128
	ds_read_b64 v[124:125], v65 offset:48128
	s_waitcnt lgkmcnt(7)
	v_add_f32_e32 v126, v110, v111
	s_waitcnt lgkmcnt(6)
	v_add_f32_e32 v127, v112, v113
	s_waitcnt lgkmcnt(5)
	v_add_f32_e32 v128, v114, v115
	s_waitcnt lgkmcnt(4)
	v_add_f32_e32 v129, v116, v117
	s_waitcnt lgkmcnt(3)
	v_add_f32_e32 v130, v118, v119
	s_waitcnt lgkmcnt(2)
	v_add_f32_e32 v131, v120, v121
	s_waitcnt lgkmcnt(1)
	v_add_f32_e32 v132, v122, v123
	s_waitcnt lgkmcnt(0)
	v_add_f32_e32 v133, v124, v125
	v_add_f32_dpp v126, v126, v126 quad_perm:[1,0,3,2] row_mask:0xf bank_mask:0xf
	v_add_f32_dpp v127, v127, v127 quad_perm:[1,0,3,2] row_mask:0xf bank_mask:0xf
	v_add_f32_dpp v128, v128, v128 quad_perm:[1,0,3,2] row_mask:0xf bank_mask:0xf
	v_add_f32_dpp v129, v129, v129 quad_perm:[1,0,3,2] row_mask:0xf bank_mask:0xf
	v_add_f32_dpp v130, v130, v130 quad_perm:[1,0,3,2] row_mask:0xf bank_mask:0xf
	v_add_f32_dpp v131, v131, v131 quad_perm:[1,0,3,2] row_mask:0xf bank_mask:0xf
	v_add_f32_dpp v132, v132, v132 quad_perm:[1,0,3,2] row_mask:0xf bank_mask:0xf
	v_add_f32_dpp v133, v133, v133 quad_perm:[1,0,3,2] row_mask:0xf bank_mask:0xf
	v_add_f32_dpp v126, v126, v126 quad_perm:[2,3,0,1] row_mask:0xf bank_mask:0xf
	v_add_f32_dpp v127, v127, v127 quad_perm:[2,3,0,1] row_mask:0xf bank_mask:0xf
	v_add_f32_dpp v128, v128, v128 quad_perm:[2,3,0,1] row_mask:0xf bank_mask:0xf
	v_add_f32_dpp v129, v129, v129 quad_perm:[2,3,0,1] row_mask:0xf bank_mask:0xf
	v_add_f32_dpp v130, v130, v130 quad_perm:[2,3,0,1] row_mask:0xf bank_mask:0xf
	v_add_f32_dpp v131, v131, v131 quad_perm:[2,3,0,1] row_mask:0xf bank_mask:0xf
	v_add_f32_dpp v132, v132, v132 quad_perm:[2,3,0,1] row_mask:0xf bank_mask:0xf
	v_add_f32_dpp v133, v133, v133 quad_perm:[2,3,0,1] row_mask:0xf bank_mask:0xf
	v_add_f32_dpp v126, v126, v126 row_half_mirror row_mask:0xf bank_mask:0xf
	v_add_f32_dpp v127, v127, v127 row_half_mirror row_mask:0xf bank_mask:0xf
	v_add_f32_dpp v128, v128, v128 row_half_mirror row_mask:0xf bank_mask:0xf
	v_add_f32_dpp v129, v129, v129 row_half_mirror row_mask:0xf bank_mask:0xf
	v_add_f32_dpp v130, v130, v130 row_half_mirror row_mask:0xf bank_mask:0xf
	v_add_f32_dpp v131, v131, v131 row_half_mirror row_mask:0xf bank_mask:0xf
	v_add_f32_dpp v132, v132, v132 row_half_mirror row_mask:0xf bank_mask:0xf
	v_add_f32_dpp v133, v133, v133 row_half_mirror row_mask:0xf bank_mask:0xf
	v_add_f32_dpp v126, v126, v126 row_mirror row_mask:0xf bank_mask:0xf
	v_add_f32_dpp v127, v127, v127 row_mirror row_mask:0xf bank_mask:0xf
	v_add_f32_dpp v128, v128, v128 row_mirror row_mask:0xf bank_mask:0xf
	v_add_f32_dpp v129, v129, v129 row_mirror row_mask:0xf bank_mask:0xf
	v_add_f32_dpp v130, v130, v130 row_mirror row_mask:0xf bank_mask:0xf
	v_add_f32_dpp v131, v131, v131 row_mirror row_mask:0xf bank_mask:0xf
	v_add_f32_dpp v132, v132, v132 row_mirror row_mask:0xf bank_mask:0xf
	v_add_f32_dpp v133, v133, v133 row_mirror row_mask:0xf bank_mask:0xf
	v_mov_b32_e32 v134, v126
	v_mov_b32_e32 v135, v127
	v_mov_b32_e32 v136, v128
	v_mov_b32_e32 v137, v129
	v_mov_b32_e32 v138, v130
	v_mov_b32_e32 v139, v131
	v_mov_b32_e32 v140, v132
	v_mov_b32_e32 v141, v133
	v_permlane16_swap_b32 v126, v134
	v_permlane16_swap_b32 v127, v135
	v_permlane16_swap_b32 v128, v136
	v_permlane16_swap_b32 v129, v137
	v_permlane16_swap_b32 v130, v138
	v_permlane16_swap_b32 v131, v139
	v_permlane16_swap_b32 v132, v140
	v_permlane16_swap_b32 v133, v141
	v_add_f32_e32 v126, v126, v134
	v_add_f32_e32 v127, v127, v135
	v_add_f32_e32 v128, v128, v136
	v_add_f32_e32 v129, v129, v137
	v_add_f32_e32 v130, v130, v138
	v_add_f32_e32 v131, v131, v139
	v_add_f32_e32 v132, v132, v140
	v_add_f32_e32 v133, v133, v141
; __device__ __forceinline__ void conv_phase(LAS unsigned char* lds, const bf16_t* P, const float* cw, const float* cb, const float* ng, const float* nb, bf16_t* CAT, int bid, int G, const int tid) {
;     ...
;                 const float mean = wave_sum(v[0] + v[1]) * (1.0f / 128.0f);
;                 const float d0 = v[0] - mean, d1 = v[1] - mean;
;                 const float rs = __builtin_amdgcn_rsqf(wave_sum(d0 * d0 + d1 * d1) * (1.0f / 128.0f) + EPS);
	v_mov_b32_e32 v134, v126
	v_mov_b32_e32 v135, v127
	v_mov_b32_e32 v136, v128
	v_mov_b32_e32 v137, v129
	v_mov_b32_e32 v138, v130
	v_mov_b32_e32 v139, v131
	v_mov_b32_e32 v140, v132
	v_mov_b32_e32 v141, v133
	v_permlane32_swap_b32 v126, v134
	v_permlane32_swap_b32 v127, v135
	v_permlane32_swap_b32 v128, v136
	v_permlane32_swap_b32 v129, v137
	v_permlane32_swap_b32 v130, v138
	v_permlane32_swap_b32 v131, v139
	v_permlane32_swap_b32 v132, v140
	v_permlane32_swap_b32 v133, v141
	v_add_f32_e32 v126, v126, v134
	v_add_f32_e32 v127, v127, v135
	v_add_f32_e32 v128, v128, v136
	v_add_f32_e32 v129, v129, v137
	v_add_f32_e32 v130, v130, v138
	v_add_f32_e32 v131, v131, v139
	v_add_f32_e32 v132, v132, v140
	v_add_f32_e32 v133, v133, v141
	v_fmac_f32_e32 v111, 0xbc000000, v126
	v_fmamk_f32 v110, v126, 0xbc000000, v110
	v_fmac_f32_e32 v113, 0xbc000000, v127
	v_fmamk_f32 v112, v127, 0xbc000000, v112
	v_fmac_f32_e32 v115, 0xbc000000, v128
	v_fmamk_f32 v114, v128, 0xbc000000, v114
	v_fmac_f32_e32 v117, 0xbc000000, v129
	v_fmamk_f32 v116, v129, 0xbc000000, v116
	v_fmac_f32_e32 v119, 0xbc000000, v130
	v_fmamk_f32 v118, v130, 0xbc000000, v118
	v_fmac_f32_e32 v121, 0xbc000000, v131
	v_fmamk_f32 v120, v131, 0xbc000000, v120
	v_fmac_f32_e32 v123, 0xbc000000, v132
	v_fmamk_f32 v122, v132, 0xbc000000, v122
	v_fmac_f32_e32 v125, 0xbc000000, v133
	v_fmamk_f32 v124, v133, 0xbc000000, v124
	v_mul_f32_e32 v126, v111, v111
	v_fmac_f32_e32 v126, v110, v110
	v_mul_f32_e32 v127, v113, v113
	v_fmac_f32_e32 v127, v112, v112
	v_mul_f32_e32 v128, v115, v115
	v_fmac_f32_e32 v128, v114, v114
	v_mul_f32_e32 v129, v117, v117
	v_fmac_f32_e32 v129, v116, v116
	v_mul_f32_e32 v130, v119, v119
	v_fmac_f32_e32 v130, v118, v118
	v_mul_f32_e32 v131, v121, v121
	v_fmac_f32_e32 v131, v120, v120
	v_mul_f32_e32 v132, v123, v123
	v_fmac_f32_e32 v132, v122, v122
	v_mul_f32_e32 v133, v125, v125
	v_fmac_f32_e32 v133, v124, v124
	v_add_f32_dpp v126, v126, v126 quad_perm:[1,0,3,2] row_mask:0xf bank_mask:0xf
	v_add_f32_dpp v127, v127, v127 quad_perm:[1,0,3,2] row_mask:0xf bank_mask:0xf
	v_add_f32_dpp v128, v128, v128 quad_perm:[1,0,3,2] row_mask:0xf bank_mask:0xf
	v_add_f32_dpp v129, v129, v129 quad_perm:[1,0,3,2] row_mask:0xf bank_mask:0xf
	v_add_f32_dpp v130, v130, v130 quad_perm:[1,0,3,2] row_mask:0xf bank_mask:0xf
	v_add_f32_dpp v131, v131, v131 quad_perm:[1,0,3,2] row_mask:0xf bank_mask:0xf
	v_add_f32_dpp v132, v132, v132 quad_perm:[1,0,3,2] row_mask:0xf bank_mask:0xf
	v_add_f32_dpp v133, v133, v133 quad_perm:[1,0,3,2] row_mask:0xf bank_mask:0xf
	v_add_f32_dpp v126, v126, v126 quad_perm:[2,3,0,1] row_mask:0xf bank_mask:0xf
	v_add_f32_dpp v127, v127, v127 quad_perm:[2,3,0,1] row_mask:0xf bank_mask:0xf
	v_add_f32_dpp v128, v128, v128 quad_perm:[2,3,0,1] row_mask:0xf bank_mask:0xf
	v_add_f32_dpp v129, v129, v129 quad_perm:[2,3,0,1] row_mask:0xf bank_mask:0xf
	v_add_f32_dpp v130, v130, v130 quad_perm:[2,3,0,1] row_mask:0xf bank_mask:0xf
	v_add_f32_dpp v131, v131, v131 quad_perm:[2,3,0,1] row_mask:0xf bank_mask:0xf
	v_add_f32_dpp v132, v132, v132 quad_perm:[2,3,0,1] row_mask:0xf bank_mask:0xf
	v_add_f32_dpp v133, v133, v133 quad_perm:[2,3,0,1] row_mask:0xf bank_mask:0xf
	v_add_f32_dpp v126, v126, v126 row_half_mirror row_mask:0xf bank_mask:0xf
	v_add_f32_dpp v127, v127, v127 row_half_mirror row_mask:0xf bank_mask:0xf
	v_add_f32_dpp v128, v128, v128 row_half_mirror row_mask:0xf bank_mask:0xf
	v_add_f32_dpp v129, v129, v129 row_half_mirror row_mask:0xf bank_mask:0xf
	v_add_f32_dpp v130, v130, v130 row_half_mirror row_mask:0xf bank_mask:0xf
	v_add_f32_dpp v131, v131, v131 row_half_mirror row_mask:0xf bank_mask:0xf
	v_add_f32_dpp v132, v132, v132 row_half_mirror row_mask:0xf bank_mask:0xf
	v_add_f32_dpp v133, v133, v133 row_half_mirror row_mask:0xf bank_mask:0xf
	v_add_f32_dpp v126, v126, v126 row_mirror row_mask:0xf bank_mask:0xf
	v_add_f32_dpp v127, v127, v127 row_mirror row_mask:0xf bank_mask:0xf
	v_add_f32_dpp v128, v128, v128 row_mirror row_mask:0xf bank_mask:0xf
	v_add_f32_dpp v129, v129, v129 row_mirror row_mask:0xf bank_mask:0xf
	v_add_f32_dpp v130, v130, v130 row_mirror row_mask:0xf bank_mask:0xf
	v_add_f32_dpp v131, v131, v131 row_mirror row_mask:0xf bank_mask:0xf
	v_add_f32_dpp v132, v132, v132 row_mirror row_mask:0xf bank_mask:0xf
	v_add_f32_dpp v133, v133, v133 row_mirror row_mask:0xf bank_mask:0xf
	v_mov_b32_e32 v134, v126
	v_mov_b32_e32 v135, v127
	v_mov_b32_e32 v136, v128
	v_mov_b32_e32 v137, v129
	v_mov_b32_e32 v138, v130
	v_mov_b32_e32 v139, v131
	v_mov_b32_e32 v140, v132
	v_mov_b32_e32 v141, v133
	v_permlane16_swap_b32 v126, v134
	v_permlane16_swap_b32 v127, v135
	v_permlane16_swap_b32 v128, v136
	v_permlane16_swap_b32 v129, v137
	v_permlane16_swap_b32 v130, v138
	v_permlane16_swap_b32 v131, v139
	v_permlane16_swap_b32 v132, v140
	v_permlane16_swap_b32 v133, v141
	v_add_f32_e32 v126, v126, v134
	v_add_f32_e32 v127, v127, v135
	v_add_f32_e32 v128, v128, v136
	v_add_f32_e32 v129, v129, v137
	v_add_f32_e32 v130, v130, v138
	v_add_f32_e32 v131, v131, v139
	v_add_f32_e32 v132, v132, v140
	v_add_f32_e32 v133, v133, v141
	v_mov_b32_e32 v134, v126
	v_mov_b32_e32 v135, v127
	v_mov_b32_e32 v136, v128
	v_mov_b32_e32 v137, v129
	v_mov_b32_e32 v138, v130
	v_mov_b32_e32 v139, v131
	v_mov_b32_e32 v140, v132
	v_mov_b32_e32 v141, v133
	v_permlane32_swap_b32 v126, v134
	v_permlane32_swap_b32 v127, v135
	v_permlane32_swap_b32 v128, v136
	v_permlane32_swap_b32 v129, v137
	v_permlane32_swap_b32 v130, v138
	v_permlane32_swap_b32 v131, v139
	v_permlane32_swap_b32 v132, v140
	v_permlane32_swap_b32 v133, v141
	v_add_f32_e32 v126, v126, v134
	v_add_f32_e32 v127, v127, v135
	v_add_f32_e32 v128, v128, v136
; __device__ __forceinline__ unsigned cvt_pk_bf16(float lo, float hi) { unsigned r; asm("v_cvt_pk_bf16_f32 %0, %1, %2" : "=v"(r) : "v"(lo), "v"(hi)); return r; }
; __device__ __forceinline__ float silu_f(float x) { return x * fast_sigmoid(x); }
; __device__ __forceinline__ void conv_phase(LAS unsigned char* lds, const bf16_t* P, const float* cw, const float* cb, const float* ng, const float* nb, bf16_t* CAT, int bid, int G, const int tid) {
;     ...
;                 const float mean = wave_sum(v[0] + v[1]) * (1.0f / 128.0f);
;                 const float d0 = v[0] - mean, d1 = v[1] - mean;
;                 const float rs = __builtin_amdgcn_rsqf(wave_sum(d0 * d0 + d1 * d1) * (1.0f / 128.0f) + EPS);
;                 const float y0 = d0 * rs * gg[0] + bb[0], y1 = d1 * rs * gg[1] + bb[1];
;                 *(unsigned*)(CAT + (size_t)(b * SEQ + t0 + tok) * D + 1024 + g * 128 + 2 * lane) = cvt_pk_bf16(silu_f(y0), silu_f(y1));
	v_add_f32_e32 v129, v129, v137
	v_add_f32_e32 v130, v130, v138
	v_add_f32_e32 v131, v131, v139
	v_add_f32_e32 v132, v132, v140
	v_add_f32_e32 v133, v133, v141
	v_fmamk_f32 v126, v126, 0x3c000000, v189
	v_fmamk_f32 v127, v127, 0x3c000000, v189
	v_fmamk_f32 v128, v128, 0x3c000000, v189
	v_fmamk_f32 v129, v129, 0x3c000000, v189
	v_fmamk_f32 v130, v130, 0x3c000000, v189
	v_fmamk_f32 v131, v131, 0x3c000000, v189
	v_fmamk_f32 v132, v132, 0x3c000000, v189
	v_fmamk_f32 v133, v133, 0x3c000000, v189
	v_rsq_f32_e32 v126, v126
	v_rsq_f32_e32 v127, v127
	v_rsq_f32_e32 v128, v128
	v_rsq_f32_e32 v129, v129
	v_rsq_f32_e32 v130, v130
	v_rsq_f32_e32 v131, v131
	v_rsq_f32_e32 v132, v132
	v_rsq_f32_e32 v133, v133
	v_mul_f32_e32 v110, v110, v126
	v_mul_f32_e32 v111, v111, v126
	v_mul_f32_e32 v112, v112, v127
	v_mul_f32_e32 v113, v113, v127
	v_mul_f32_e32 v114, v114, v128
	v_mul_f32_e32 v115, v115, v128
	v_mul_f32_e32 v116, v116, v129
	v_mul_f32_e32 v117, v117, v129
	v_mul_f32_e32 v118, v118, v130
	v_mul_f32_e32 v119, v119, v130
	v_mul_f32_e32 v120, v120, v131
	v_mul_f32_e32 v121, v121, v131
	v_mul_f32_e32 v122, v122, v132
	v_mul_f32_e32 v123, v123, v132
	v_mul_f32_e32 v124, v124, v133
	v_mul_f32_e32 v125, v125, v133
	v_fma_f32 v110, v150, v110, v152
	v_fma_f32 v111, v151, v111, v153
	v_fma_f32 v112, v150, v112, v152
	v_fma_f32 v113, v151, v113, v153
	v_fma_f32 v114, v150, v114, v152
	v_fma_f32 v115, v151, v115, v153
	v_fma_f32 v116, v150, v116, v152
	v_fma_f32 v117, v151, v117, v153
	v_fma_f32 v118, v150, v118, v152
	v_fma_f32 v119, v151, v119, v153
	v_fma_f32 v120, v150, v120, v152
	v_fma_f32 v121, v151, v121, v153
	v_fma_f32 v122, v150, v122, v152
	v_fma_f32 v123, v151, v123, v153
	v_fma_f32 v124, v150, v124, v152
	v_fma_f32 v125, v151, v125, v153
	v_mul_f32_e32 v134, 0xbfb8aa3b, v110
	v_mul_f32_e32 v142, 0xbfb8aa3b, v111
	v_mul_f32_e32 v135, 0xbfb8aa3b, v112
	v_mul_f32_e32 v143, 0xbfb8aa3b, v113
	v_mul_f32_e32 v136, 0xbfb8aa3b, v114
	v_mul_f32_e32 v144, 0xbfb8aa3b, v115
	v_mul_f32_e32 v137, 0xbfb8aa3b, v116
	v_mul_f32_e32 v145, 0xbfb8aa3b, v117
	v_mul_f32_e32 v138, 0xbfb8aa3b, v118
	v_mul_f32_e32 v146, 0xbfb8aa3b, v119
	v_mul_f32_e32 v139, 0xbfb8aa3b, v120
	v_mul_f32_e32 v147, 0xbfb8aa3b, v121
	v_mul_f32_e32 v140, 0xbfb8aa3b, v122
	v_mul_f32_e32 v148, 0xbfb8aa3b, v123
	v_mul_f32_e32 v141, 0xbfb8aa3b, v124
	v_mul_f32_e32 v149, 0xbfb8aa3b, v125
	v_exp_f32_e32 v134, v134
	v_exp_f32_e32 v142, v142
	v_exp_f32_e32 v135, v135
	v_exp_f32_e32 v143, v143
	v_exp_f32_e32 v136, v136
	v_exp_f32_e32 v144, v144
	v_exp_f32_e32 v137, v137
	v_exp_f32_e32 v145, v145
	v_exp_f32_e32 v138, v138
	v_exp_f32_e32 v146, v146
	v_exp_f32_e32 v139, v139
	v_exp_f32_e32 v147, v147
	v_exp_f32_e32 v140, v140
	v_exp_f32_e32 v148, v148
	v_exp_f32_e32 v141, v141
	v_exp_f32_e32 v149, v149
	s_nop 0
	v_add_f32_e32 v134, 1.0, v134
	v_add_f32_e32 v142, 1.0, v142
	v_add_f32_e32 v135, 1.0, v135
	v_add_f32_e32 v143, 1.0, v143
	v_add_f32_e32 v136, 1.0, v136
	v_add_f32_e32 v144, 1.0, v144
	v_add_f32_e32 v137, 1.0, v137
	v_add_f32_e32 v145, 1.0, v145
	v_add_f32_e32 v138, 1.0, v138
	v_add_f32_e32 v146, 1.0, v146
	v_add_f32_e32 v139, 1.0, v139
	v_add_f32_e32 v147, 1.0, v147
	v_add_f32_e32 v140, 1.0, v140
	v_add_f32_e32 v148, 1.0, v148
	v_add_f32_e32 v141, 1.0, v141
	v_add_f32_e32 v149, 1.0, v149
	v_rcp_f32_e32 v134, v134
	v_rcp_f32_e32 v142, v142
	v_rcp_f32_e32 v135, v135
	v_rcp_f32_e32 v143, v143
	v_rcp_f32_e32 v136, v136
	v_rcp_f32_e32 v144, v144
	v_rcp_f32_e32 v137, v137
	v_rcp_f32_e32 v145, v145
	v_rcp_f32_e32 v138, v138
	v_rcp_f32_e32 v146, v146
	v_rcp_f32_e32 v139, v139
	v_rcp_f32_e32 v147, v147
	v_rcp_f32_e32 v140, v140
	v_rcp_f32_e32 v148, v148
	v_rcp_f32_e32 v141, v141
	v_rcp_f32_e32 v149, v149
	s_nop 0
	v_mul_f32_e32 v110, v110, v134
	v_mul_f32_e32 v111, v111, v142
	v_mul_f32_e32 v112, v112, v135
	v_mul_f32_e32 v113, v113, v143
	v_mul_f32_e32 v114, v114, v136
	v_mul_f32_e32 v115, v115, v144
	v_mul_f32_e32 v116, v116, v137
	v_mul_f32_e32 v117, v117, v145
	v_mul_f32_e32 v118, v118, v138
	v_mul_f32_e32 v119, v119, v146
	v_mul_f32_e32 v120, v120, v139
	v_mul_f32_e32 v121, v121, v147
	v_mul_f32_e32 v122, v122, v140
	v_mul_f32_e32 v123, v123, v148
	v_mul_f32_e32 v124, v124, v141
	v_mul_f32_e32 v125, v125, v149
	v_cvt_pk_bf16_f32 v134, v110, v111
	v_cvt_pk_bf16_f32 v135, v112, v113
	v_cvt_pk_bf16_f32 v136, v114, v115
	v_cvt_pk_bf16_f32 v137, v116, v117
	v_cvt_pk_bf16_f32 v138, v118, v119
	v_cvt_pk_bf16_f32 v139, v120, v121
	v_cvt_pk_bf16_f32 v140, v122, v123
	v_cvt_pk_bf16_f32 v141, v124, v125
	v_add_u32_e32 v66, s31, v41
	v_ashrrev_i32_e32 v67, 31, v66
	v_lshlrev_b64 v[66:67], 12, v[66:67]
	v_lshl_add_u64 v[66:67], s[92:93], 0, v[66:67]
	v_lshl_add_u64 v[66:67], v[66:67], 0, s[26:27]
	v_lshl_add_u64 v[66:67], v[66:67], 0, v[30:31]
	global_store_dword v[66:67], v134, off offset:2048
	v_add_u32_e32 v66, s31, v51
	v_ashrrev_i32_e32 v67, 31, v66
	v_lshlrev_b64 v[66:67], 12, v[66:67]
	v_lshl_add_u64 v[66:67], s[92:93], 0, v[66:67]
	v_lshl_add_u64 v[66:67], v[66:67], 0, s[26:27]
	v_lshl_add_u64 v[66:67], v[66:67], 0, v[30:31]
	global_store_dword v[66:67], v135, off offset:2048
	v_add_u32_e32 v66, s31, v52
	v_ashrrev_i32_e32 v67, 31, v66
	v_lshlrev_b64 v[66:67], 12, v[66:67]
	v_lshl_add_u64 v[66:67], s[92:93], 0, v[66:67]
	v_lshl_add_u64 v[66:67], v[66:67], 0, s[26:27]
	v_lshl_add_u64 v[66:67], v[66:67], 0, v[30:31]
	global_store_dword v[66:67], v136, off offset:2048
	v_add_u32_e32 v66, s31, v53
	v_ashrrev_i32_e32 v67, 31, v66
	v_lshlrev_b64 v[66:67], 12, v[66:67]
	v_lshl_add_u64 v[66:67], s[92:93], 0, v[66:67]
	v_lshl_add_u64 v[66:67], v[66:67], 0, s[26:27]
	v_lshl_add_u64 v[66:67], v[66:67], 0, v[30:31]
	global_store_dword v[66:67], v137, off offset:2048
	v_add_u32_e32 v66, s31, v54
	v_ashrrev_i32_e32 v67, 31, v66
	v_lshlrev_b64 v[66:67], 12, v[66:67]
	v_lshl_add_u64 v[66:67], s[92:93], 0, v[66:67]
	v_lshl_add_u64 v[66:67], v[66:67], 0, s[26:27]
	v_lshl_add_u64 v[66:67], v[66:67], 0, v[30:31]
	global_store_dword v[66:67], v138, off offset:2048
	v_add_u32_e32 v66, s31, v55
	v_ashrrev_i32_e32 v67, 31, v66
	v_lshlrev_b64 v[66:67], 12, v[66:67]
	v_lshl_add_u64 v[66:67], s[92:93], 0, v[66:67]
	v_lshl_add_u64 v[66:67], v[66:67], 0, s[26:27]
	v_lshl_add_u64 v[66:67], v[66:67], 0, v[30:31]
	global_store_dword v[66:67], v139, off offset:2048
	v_add_u32_e32 v66, s31, v56
	v_ashrrev_i32_e32 v67, 31, v66
	v_lshlrev_b64 v[66:67], 12, v[66:67]
	v_lshl_add_u64 v[66:67], s[92:93], 0, v[66:67]
	v_lshl_add_u64 v[66:67], v[66:67], 0, s[26:27]
	v_lshl_add_u64 v[66:67], v[66:67], 0, v[30:31]
	global_store_dword v[66:67], v140, off offset:2048
	v_add_u32_e32 v66, s31, v57
	v_ashrrev_i32_e32 v67, 31, v66
	v_lshlrev_b64 v[66:67], 12, v[66:67]
	v_lshl_add_u64 v[66:67], s[92:93], 0, v[66:67]
	v_lshl_add_u64 v[66:67], v[66:67], 0, s[26:27]
	v_lshl_add_u64 v[66:67], v[66:67], 0, v[30:31]
	global_store_dword v[66:67], v141, off offset:2048
	s_cbranch_vccz .LBB0_186
